# MoBA softmax tail: packed subtract, packed pairwise sum of the 16 probabilities and direct two-value bf16 packing (8 cvt) instead of 16 single cvt + 8 v_perm and a 16-long scalar add chain
# baseline (speedup 1.0000x reference)
; __device__ void moba_item(const P& p, int bh, int qt, char* smem) {
;     ...
;       float ps = 0.f;
;       bf16x8 pf[2];
; #pragma unroll
;       for (int st = 0; st < 2; ++st) {
;         float pv[8];
; #pragma unroll
;         for (int kt = 0; kt < 2; ++kt)
; #pragma unroll
;           for (int r = 0; r < 4; ++r) {
;             const float e = __builtin_amdgcn_exp2f(sacc[st][kt][r] - muse);
;             pv[kt * 4 + r] = e;
;             ps += e;
;           }
;         u32x4 u;
;         u.x = pk_bf16(pv[0], pv[1]); u.y = pk_bf16(pv[2], pv[3]); u.z = pk_bf16(pv[4], pv[5]); u.w = pk_bf16(pv[6], pv[7]);
;         pf[st] = *(bf16x8*)&u;
;       }
;       lrun = lrun * alpha + ps;
;       if (resc) {
; #pragma unroll
;         for (int d = 0; d < 8; ++d) oacc[d] *= alpha;
;       }
; #pragma unroll
;       for (int d = 0; d < 8; ++d) {
;         const int row = d * 16 + li;
; #pragma unroll
;         for (int st = 0; st < 2; ++st) {
;           const bf16x8 vf = *(const bf16x8*)(sV + row * 128 + (((st * 4 + g) ^ (li & 7)) << 4));
;           oacc[d] = __builtin_amdgcn_mfma_f32_16x16x32_bf16(vf, pf[st], oacc[d], 0, 0, 0);
;         }
;       }
.LBB0_624:
	v_add_u32_e32 v236, v181, v182
	v_add_u32_e32 v237, v181, v183
	ds_read_b128 v[194:197], v236 offset:16384
	ds_read_b128 v[198:201], v237 offset:16384
	ds_read_b128 v[202:205], v236 offset:18432
	ds_read_b128 v[220:223], v237 offset:18432
	ds_read_b128 v[224:227], v236 offset:20480
	ds_read_b128 v[228:231], v237 offset:20480
	ds_read_b128 v[232:235], v236 offset:22528
	ds_read_b128 v[4:7], v237 offset:22528
	ds_read_b128 v[8:11], v236 offset:24576
	ds_read_b128 v[12:15], v237 offset:24576
	ds_read_b128 v[16:19], v236 offset:26624
	v_pk_add_f32 v[2:3], v[2:3], v[132:133] op_sel_hi:[1,0] neg_lo:[0,1] neg_hi:[0,1]
	v_pk_add_f32 v[164:165], v[164:165], v[132:133] op_sel_hi:[1,0] neg_lo:[0,1] neg_hi:[0,1]
	v_pk_add_f32 v[166:167], v[166:167], v[132:133] op_sel_hi:[1,0] neg_lo:[0,1] neg_hi:[0,1]
	v_pk_add_f32 v[168:169], v[168:169], v[132:133] op_sel_hi:[1,0] neg_lo:[0,1] neg_hi:[0,1]
	v_pk_add_f32 v[170:171], v[170:171], v[132:133] op_sel_hi:[1,0] neg_lo:[0,1] neg_hi:[0,1]
	v_pk_add_f32 v[172:173], v[172:173], v[132:133] op_sel_hi:[1,0] neg_lo:[0,1] neg_hi:[0,1]
	v_pk_add_f32 v[174:175], v[174:175], v[132:133] op_sel_hi:[1,0] neg_lo:[0,1] neg_hi:[0,1]
	v_pk_add_f32 v[176:177], v[176:177], v[132:133] op_sel_hi:[1,0] neg_lo:[0,1] neg_hi:[0,1]
	v_exp_f32_e32 v2, v2
	v_exp_f32_e32 v3, v3
	v_exp_f32_e32 v164, v164
	v_exp_f32_e32 v165, v165
	v_exp_f32_e32 v166, v166
	v_exp_f32_e32 v167, v167
	v_exp_f32_e32 v168, v168
	v_exp_f32_e32 v169, v169
	v_exp_f32_e32 v170, v170
	v_exp_f32_e32 v171, v171
	v_exp_f32_e32 v172, v172
	v_exp_f32_e32 v173, v173
	v_exp_f32_e32 v174, v174
	v_exp_f32_e32 v175, v175
	v_exp_f32_e32 v176, v176
	v_exp_f32_e32 v177, v177
	v_pk_add_f32 v[140:141], v[2:3], v[164:165]
	v_pk_add_f32 v[142:143], v[166:167], v[168:169]
	v_pk_add_f32 v[144:145], v[170:171], v[172:173]
	v_pk_add_f32 v[146:147], v[174:175], v[176:177]
	v_pk_add_f32 v[140:141], v[140:141], v[142:143]
	v_pk_add_f32 v[144:145], v[144:145], v[146:147]
	v_pk_add_f32 v[140:141], v[140:141], v[144:145]
	s_nop 0
	v_add_f32_e32 v147, v140, v141
	v_fmac_f32_e32 v147, v188, v0
	v_cvt_pk_bf16_f32 v136, v2, v3
	v_cvt_pk_bf16_f32 v137, v164, v165
	v_cvt_pk_bf16_f32 v138, v166, v167
	v_cvt_pk_bf16_f32 v139, v168, v169
	v_cvt_pk_bf16_f32 v132, v170, v171
	v_cvt_pk_bf16_f32 v133, v172, v173
	v_cvt_pk_bf16_f32 v134, v174, v175
	v_cvt_pk_bf16_f32 v135, v176, v177
	v_mov_b32_e32 v188, v147
	v_add_u32_e32 v0, v181, v182
	v_add_u32_e32 v2, v181, v183
	s_waitcnt lgkmcnt(0)
	v_mfma_f32_16x16x32_bf16 v[108:111], v[194:197], v[136:139], v[108:111]
	v_mfma_f32_16x16x32_bf16 v[112:115], v[202:205], v[136:139], v[112:115]
	v_mfma_f32_16x16x32_bf16 v[68:71], v[224:227], v[136:139], v[68:71]
	v_mfma_f32_16x16x32_bf16 v[76:79], v[232:235], v[136:139], v[76:79]
	v_mfma_f32_16x16x32_bf16 v[60:63], v[8:11], v[136:139], v[60:63]
	ds_read_b128 v[194:197], v237 offset:26624
	ds_read_b128 v[202:205], v236 offset:28672
	ds_read_b128 v[224:227], v237 offset:28672
	ds_read_b128 v[232:235], v236 offset:30720
	ds_read_b128 v[8:11], v237 offset:30720
	v_mfma_f32_16x16x32_bf16 v[108:111], v[198:201], v[132:135], v[108:111]
	v_mfma_f32_16x16x32_bf16 v[112:115], v[220:223], v[132:135], v[112:115]
	v_mfma_f32_16x16x32_bf16 v[68:71], v[228:231], v[132:135], v[68:71]
	v_mfma_f32_16x16x32_bf16 v[76:79], v[4:7], v[132:135], v[76:79]
	v_mfma_f32_16x16x32_bf16 v[60:63], v[12:15], v[132:135], v[60:63]
	v_mfma_f32_16x16x32_bf16 v[72:75], v[16:19], v[136:139], v[72:75]
	s_waitcnt lgkmcnt(0)
	v_mfma_f32_16x16x32_bf16 v[72:75], v[194:197], v[132:135], v[72:75]
	v_mfma_f32_16x16x32_bf16 v[52:55], v[202:205], v[136:139], v[52:55]
	v_mfma_f32_16x16x32_bf16 v[104:107], v[232:235], v[136:139], v[104:107]
	v_mfma_f32_16x16x32_bf16 v[52:55], v[224:227], v[132:135], v[52:55]
	v_mfma_f32_16x16x32_bf16 v[104:107], v[8:11], v[132:135], v[104:107]
	s_cmp_ge_i32 s27, s40
	s_cbranch_scc1 .LBB0_612
	s_branch .LBB0_626

; __device__ void moba_item(const P& p, int bh, int qt, char* smem) {
;     ...
;       float ps = 0.f;
;       bf16x8 pf[2];
; #pragma unroll
;       for (int st = 0; st < 2; ++st) {
;         float pv[8];
; #pragma unroll
;         for (int kt = 0; kt < 2; ++kt)
; #pragma unroll
;           for (int r = 0; r < 4; ++r) {
;             const float e = __builtin_amdgcn_exp2f(sacc[st][kt][r] - muse);
;             pv[kt * 4 + r] = e;
;             ps += e;
;           }
;         u32x4 u;
;         u.x = pk_bf16(pv[0], pv[1]); u.y = pk_bf16(pv[2], pv[3]); u.z = pk_bf16(pv[4], pv[5]); u.w = pk_bf16(pv[6], pv[7]);
;         pf[st] = *(bf16x8*)&u;
;       }
;       lrun = lrun * alpha + ps;
;       if (resc) {
; #pragma unroll
;         for (int d = 0; d < 8; ++d) oacc[d] *= alpha;
;       }
; #pragma unroll
;       for (int d = 0; d < 8; ++d) {
;         const int row = d * 16 + li;
; #pragma unroll
;         for (int st = 0; st < 2; ++st) {
;           const bf16x8 vf = *(const bf16x8*)(sV + row * 128 + (((st * 4 + g) ^ (li & 7)) << 4));
;           oacc[d] = __builtin_amdgcn_mfma_f32_16x16x32_bf16(vf, pf[st], oacc[d], 0, 0, 0);
;         }
;       }
;     }
;     };
;   for (int tt = 0; tt < ntiles; tt += 2) {
;     step(tt, rkA, rvA);
;     if (tt + 1 < ntiles) step(tt + 1, rkB, rvB);
.LBB0_636:
	v_add_u32_e32 v236, v181, v182
	v_add_u32_e32 v237, v181, v183
	ds_read_b128 v[194:197], v236 offset:49152
	ds_read_b128 v[198:201], v237 offset:49152
	ds_read_b128 v[202:205], v236 offset:51200
	ds_read_b128 v[220:223], v237 offset:51200
	ds_read_b128 v[224:227], v236 offset:53248
	ds_read_b128 v[228:231], v237 offset:53248
	ds_read_b128 v[232:235], v236 offset:55296
	ds_read_b128 v[4:7], v237 offset:55296
	ds_read_b128 v[8:11], v236 offset:57344
	ds_read_b128 v[12:15], v237 offset:57344
	ds_read_b128 v[16:19], v236 offset:59392
	v_pk_add_f32 v[2:3], v[2:3], v[132:133] op_sel_hi:[1,0] neg_lo:[0,1] neg_hi:[0,1]
	v_pk_add_f32 v[164:165], v[164:165], v[132:133] op_sel_hi:[1,0] neg_lo:[0,1] neg_hi:[0,1]
	v_pk_add_f32 v[166:167], v[166:167], v[132:133] op_sel_hi:[1,0] neg_lo:[0,1] neg_hi:[0,1]
	v_pk_add_f32 v[168:169], v[168:169], v[132:133] op_sel_hi:[1,0] neg_lo:[0,1] neg_hi:[0,1]
	v_pk_add_f32 v[170:171], v[170:171], v[132:133] op_sel_hi:[1,0] neg_lo:[0,1] neg_hi:[0,1]
	v_pk_add_f32 v[172:173], v[172:173], v[132:133] op_sel_hi:[1,0] neg_lo:[0,1] neg_hi:[0,1]
	v_pk_add_f32 v[174:175], v[174:175], v[132:133] op_sel_hi:[1,0] neg_lo:[0,1] neg_hi:[0,1]
	v_pk_add_f32 v[176:177], v[176:177], v[132:133] op_sel_hi:[1,0] neg_lo:[0,1] neg_hi:[0,1]
	v_exp_f32_e32 v2, v2
	v_exp_f32_e32 v3, v3
	v_exp_f32_e32 v164, v164
	v_exp_f32_e32 v165, v165
	v_exp_f32_e32 v166, v166
	v_exp_f32_e32 v167, v167
	v_exp_f32_e32 v168, v168
	v_exp_f32_e32 v169, v169
	v_exp_f32_e32 v170, v170
	v_exp_f32_e32 v171, v171
	v_exp_f32_e32 v172, v172
	v_exp_f32_e32 v173, v173
	v_exp_f32_e32 v174, v174
	v_exp_f32_e32 v175, v175
	v_exp_f32_e32 v176, v176
	v_exp_f32_e32 v177, v177
	v_pk_add_f32 v[140:141], v[2:3], v[164:165]
	v_pk_add_f32 v[142:143], v[166:167], v[168:169]
	v_pk_add_f32 v[144:145], v[170:171], v[172:173]
	v_pk_add_f32 v[146:147], v[174:175], v[176:177]
	v_pk_add_f32 v[140:141], v[140:141], v[142:143]
	v_pk_add_f32 v[144:145], v[144:145], v[146:147]
	v_pk_add_f32 v[140:141], v[140:141], v[144:145]
	s_nop 0
	v_add_f32_e32 v147, v140, v141
	v_fmac_f32_e32 v147, v188, v0
	v_cvt_pk_bf16_f32 v136, v2, v3
	v_cvt_pk_bf16_f32 v137, v164, v165
	v_cvt_pk_bf16_f32 v138, v166, v167
	v_cvt_pk_bf16_f32 v139, v168, v169
	v_cvt_pk_bf16_f32 v132, v170, v171
	v_cvt_pk_bf16_f32 v133, v172, v173
	v_cvt_pk_bf16_f32 v134, v174, v175
	v_cvt_pk_bf16_f32 v135, v176, v177
	v_mov_b32_e32 v188, v147
	v_add_u32_e32 v0, v181, v182
	v_add_u32_e32 v2, v181, v183
	s_waitcnt lgkmcnt(0)
	v_mfma_f32_16x16x32_bf16 v[108:111], v[194:197], v[136:139], v[108:111]
	v_mfma_f32_16x16x32_bf16 v[112:115], v[202:205], v[136:139], v[112:115]
	v_mfma_f32_16x16x32_bf16 v[68:71], v[224:227], v[136:139], v[68:71]
	v_mfma_f32_16x16x32_bf16 v[76:79], v[232:235], v[136:139], v[76:79]
	v_mfma_f32_16x16x32_bf16 v[60:63], v[8:11], v[136:139], v[60:63]
	ds_read_b128 v[194:197], v237 offset:59392
	ds_read_b128 v[202:205], v236 offset:61440
	ds_read_b128 v[224:227], v237 offset:61440
	ds_read_b128 v[232:235], v236 offset:63488
	ds_read_b128 v[8:11], v237 offset:63488
	v_mfma_f32_16x16x32_bf16 v[108:111], v[198:201], v[132:135], v[108:111]
	v_mfma_f32_16x16x32_bf16 v[112:115], v[220:223], v[132:135], v[112:115]
	v_mfma_f32_16x16x32_bf16 v[68:71], v[228:231], v[132:135], v[68:71]
	v_mfma_f32_16x16x32_bf16 v[76:79], v[4:7], v[132:135], v[76:79]
	v_mfma_f32_16x16x32_bf16 v[60:63], v[12:15], v[132:135], v[60:63]
	v_mfma_f32_16x16x32_bf16 v[72:75], v[16:19], v[136:139], v[72:75]
	s_waitcnt lgkmcnt(0)
	v_mfma_f32_16x16x32_bf16 v[72:75], v[194:197], v[132:135], v[72:75]
	v_mfma_f32_16x16x32_bf16 v[52:55], v[202:205], v[136:139], v[52:55]
	v_mfma_f32_16x16x32_bf16 v[104:107], v[232:235], v[136:139], v[104:107]
	v_mfma_f32_16x16x32_bf16 v[52:55], v[224:227], v[132:135], v[52:55]
	v_mfma_f32_16x16x32_bf16 v[104:107], v[8:11], v[132:135], v[104:107]
	s_andn2_b64 vcc, exec, s[8:9]
	s_addk_i32 s25, 0x80
	s_cbranch_vccnz .LBB0_613
	s_branch .LBB0_454
